# v27 with all 24 dead t==0 selects of the scan loader loop folded away (9 more removed, 6 become plain moves, compare deleted)
# baseline (speedup 1.0000x reference)
.Lcis_a_done:
	v_lshlrev_b32_e32 v156, 16, v104
	v_and_b32_e32 v104, 0xffff0000, v104
	v_lshlrev_b32_e32 v178, 16, v105
	v_and_b32_e32 v105, 0xffff0000, v105
	v_lshlrev_b32_e32 v179, 16, v106
	v_and_b32_e32 v106, 0xffff0000, v106
	v_lshlrev_b32_e32 v180, 16, v107
	v_and_b32_e32 v107, 0xffff0000, v107
	v_lshlrev_b32_e32 v162, 16, v100
	v_and_b32_e32 v163, 0xffff0000, v100
	v_lshlrev_b32_e32 v176, 16, v101
	v_and_b32_e32 v177, 0xffff0000, v101
	v_lshlrev_b32_e32 v100, 16, v102
	v_and_b32_e32 v101, 0xffff0000, v102
	v_lshlrev_b32_e32 v102, 16, v103
	v_and_b32_e32 v103, 0xffff0000, v103
	v_mov_b32_e32 v182, v179
	v_sub_f32_e32 v181, v107, v103
	v_sub_f32_e32 v107, v105, v177
	v_sub_f32_e32 v105, v104, v163
	v_sub_f32_e32 v104, v156, v162
	v_sub_f32_e32 v179, v106, v101
	v_sub_f32_e32 v106, v178, v176
	v_sub_f32_e32 v178, v182, v100
	v_sub_f32_e32 v180, v180, v102
	v_pk_fma_f32 v[102:103], v[38:39], v[180:181], v[102:103]
	v_pk_fma_f32 v[100:101], v[36:37], v[178:179], v[100:101]
	v_pk_fma_f32 v[106:107], v[34:35], v[106:107], v[176:177]
	s_and_b64 vcc, exec, s[44:45]
	v_pk_fma_f32 v[104:105], v[32:33], v[104:105], v[162:163]
	s_cbranch_vccnz .LBB0_210
	v_lshlrev_b32_e32 v156, 16, v92
	v_and_b32_e32 v92, 0xffff0000, v92
	v_lshlrev_b32_e32 v162, 16, v93
	v_and_b32_e32 v163, 0xffff0000, v93
	v_lshlrev_b32_e32 v176, 16, v94
	v_and_b32_e32 v177, 0xffff0000, v94
	v_lshlrev_b32_e32 v178, 16, v95
	v_and_b32_e32 v179, 0xffff0000, v95
	v_sub_f32_e32 v93, v92, v105
	v_sub_f32_e32 v92, v156, v104
	v_sub_f32_e32 v95, v163, v107
	v_sub_f32_e32 v94, v162, v106
	v_sub_f32_e32 v163, v177, v101
	v_sub_f32_e32 v162, v176, v100
	v_sub_f32_e32 v177, v179, v103
	v_sub_f32_e32 v176, v178, v102
	v_lshlrev_b32_e32 v178, 16, v88
	v_and_b32_e32 v179, 0xffff0000, v88
	v_lshlrev_b32_e32 v88, 16, v89
	v_and_b32_e32 v89, 0xffff0000, v89
	v_lshlrev_b32_e32 v180, 16, v90
	v_and_b32_e32 v181, 0xffff0000, v90
	v_lshlrev_b32_e32 v90, 16, v91
	v_and_b32_e32 v91, 0xffff0000, v91
	v_pk_fma_f32 v[102:103], v[176:177], v[90:91], v[102:103]
	v_pk_fma_f32 v[100:101], v[162:163], v[180:181], v[100:101]
	v_pk_fma_f32 v[106:107], v[94:95], v[88:89], v[106:107]
	v_pk_fma_f32 v[104:105], v[92:93], v[178:179], v[104:105]
.LBB0_210:
	v_lshlrev_b32_e32 v163, 16, v62
	v_and_b32_e32 v62, 0xffff0000, v62
	v_lshlrev_b32_e32 v176, 16, v63
	v_and_b32_e32 v63, 0xffff0000, v63
	v_lshlrev_b32_e32 v177, 16, v56
	v_and_b32_e32 v56, 0xffff0000, v56
	v_lshlrev_b32_e32 v178, 16, v57
	v_and_b32_e32 v57, 0xffff0000, v57
	v_lshlrev_b32_e32 v179, 16, v58
	v_and_b32_e32 v58, 0xffff0000, v58
	v_lshlrev_b32_e32 v180, 16, v59
	v_and_b32_e32 v59, 0xffff0000, v59
	v_lshlrev_b32_e32 v90, 16, v70
	v_and_b32_e32 v91, 0xffff0000, v70
	v_lshlrev_b32_e32 v70, 16, v71
	v_and_b32_e32 v71, 0xffff0000, v71
	v_mov_b32_e32 v181, v57
	v_mov_b32_e32 v182, v59
	v_mov_b32_e32 v183, v56
	v_mov_b32_e32 v184, v58
	v_lshlrev_b32_e32 v92, 16, v64
	v_and_b32_e32 v93, 0xffff0000, v64
	v_lshlrev_b32_e32 v94, 16, v66
	v_and_b32_e32 v95, 0xffff0000, v66
	v_sub_f32_e32 v57, v62, v91
	v_sub_f32_e32 v56, v163, v90
	v_sub_f32_e32 v59, v63, v71
	v_sub_f32_e32 v58, v176, v70
	v_lshlrev_b32_e32 v64, 16, v65
	v_and_b32_e32 v65, 0xffff0000, v65
	v_lshlrev_b32_e32 v66, 16, v67
	v_and_b32_e32 v67, 0xffff0000, v67
	v_lshlrev_b32_e32 v162, 16, v61
	v_pk_fma_f32 v[58:59], v[30:31], v[58:59], v[70:71]
	v_pk_fma_f32 v[56:57], v[28:29], v[56:57], v[90:91]
	v_sub_f32_e32 v71, v184, v95
	v_sub_f32_e32 v70, v179, v94
	v_sub_f32_e32 v91, v183, v93
	v_sub_f32_e32 v90, v177, v92
	v_mov_b32_e32 v62, v162
	v_sub_f32_e32 v163, v182, v67
	v_sub_f32_e32 v162, v180, v66
	v_sub_f32_e32 v177, v181, v65
	v_sub_f32_e32 v176, v178, v64
	v_pk_fma_f32 v[92:93], v[24:25], v[90:91], v[92:93]
	v_pk_fma_f32 v[90:91], v[20:21], v[70:71], v[94:95]
	v_pk_fma_f32 v[176:177], v[26:27], v[176:177], v[64:65]
	v_pk_fma_f32 v[162:163], v[22:23], v[162:163], v[66:67]
	v_pk_mul_f32 v[70:71], v[16:17], v[90:91]
	v_pk_mul_f32 v[94:95], v[12:13], v[92:93]
	v_pk_mul_f32 v[178:179], v[18:19], v[162:163]
	v_pk_mul_f32 v[180:181], v[14:15], v[176:177]
	v_pk_mul_f32 v[182:183], v[94:95], v[94:95]
	v_pk_mul_f32 v[184:185], v[70:71], v[70:71]
	v_pk_mul_f32 v[64:65], v[180:181], v[180:181]
	v_pk_mul_f32 v[66:67], v[178:179], v[178:179]
	v_mov_b32_e32 v186, v182
	v_mov_b32_e32 v187, v184
	v_mov_b32_e32 v184, v183
	v_pk_add_f32 v[182:183], v[186:187], v[184:185]
	v_mov_b32_e32 v184, v64
	v_mov_b32_e32 v185, v66
	v_mov_b32_e32 v66, v65
	v_pk_add_f32 v[64:65], v[184:185], v[66:67]
	v_and_b32_e32 v61, 0xffff0000, v61
	v_pk_add_f32 v[64:65], v[182:183], v[64:65]
	v_lshlrev_b32_e32 v88, 16, v68
	v_add_f32_e32 v64, v64, v65
	ds_bpermute_b32 v65, v165, v64
	v_and_b32_e32 v89, 0xffff0000, v68
	v_lshlrev_b32_e32 v68, 16, v69
	v_and_b32_e32 v69, 0xffff0000, v69
	v_lshlrev_b32_e32 v156, 16, v60
	v_and_b32_e32 v60, 0xffff0000, v60
	v_sub_f32_e32 v63, v61, v69
	v_sub_f32_e32 v62, v62, v68
	v_sub_f32_e32 v61, v60, v89
	v_sub_f32_e32 v60, v156, v88
	v_pk_fma_f32 v[62:63], v[10:11], v[62:63], v[68:69]
	v_lshlrev_b32_e32 v69, 16, v44
	v_and_b32_e32 v156, 0xffff0000, v44
	s_waitcnt lgkmcnt(0)
	v_add_f32_e32 v44, v64, v65
	ds_bpermute_b32 v64, v166, v44
	v_lshlrev_b32_e32 v192, 16, v45
	v_and_b32_e32 v193, 0xffff0000, v45
	v_lshlrev_b32_e32 v194, 16, v46
	v_and_b32_e32 v195, 0xffff0000, v46
	s_waitcnt lgkmcnt(0)
	v_add_f32_e32 v44, v44, v64
	ds_bpermute_b32 v45, v167, v44
	v_lshlrev_b32_e32 v202, 16, v47
	v_and_b32_e32 v203, 0xffff0000, v47
	v_lshlrev_b32_e32 v46, 16, v40
	v_and_b32_e32 v47, 0xffff0000, v40
	s_waitcnt lgkmcnt(0)
	v_add_f32_e32 v40, v44, v45
	v_mul_f32_e32 v44, 0x4f800000, v40
	v_cmp_gt_f32_e32 vcc, s76, v40
	v_lshlrev_b32_e32 v184, 16, v42
	v_and_b32_e32 v185, 0xffff0000, v42
	v_cndmask_b32_e32 v44, v40, v44, vcc
	v_sqrt_f32_e32 v45, v44
	v_lshlrev_b32_e32 v182, 16, v43
	v_and_b32_e32 v183, 0xffff0000, v43
	v_lshlrev_b32_e32 v40, 16, v41
	v_add_u32_e32 v64, -1, v45
	v_fma_f32 v65, -v64, v45, v44
	v_cmp_ge_f32_e64 s[48:49], 0, v65
	v_add_u32_e32 v65, 1, v45
	v_and_b32_e32 v41, 0xffff0000, v41
	v_cndmask_b32_e64 v64, v45, v64, s[48:49]
	v_fma_f32 v45, -v65, v45, v44
	v_cmp_lt_f32_e64 s[48:49], 0, v45
	s_bitcmp1_b32 s19, 0
	v_pk_add_f32 v[66:67], v[46:47], -1.0 op_sel_hi:[1,0]
	v_cndmask_b32_e64 v45, v64, v65, s[48:49]
	v_mul_f32_e32 v64, 0x37800000, v45
	v_cndmask_b32_e32 v45, v45, v64, vcc
	v_cmp_class_f32_e32 vcc, v44, v196
	v_pk_fma_f32 v[60:61], v[8:9], v[60:61], v[88:89]
	v_pk_fma_f32 v[88:89], v[4:5], v[66:67], 1.0 op_sel_hi:[1,1,0]
	v_cndmask_b32_e32 v44, v45, v44, vcc
	v_max_f32_e32 v44, 0x2b8cbccc, v44
	v_div_scale_f32 v45, s[22:23], v44, v44, 1.0
	v_rcp_f32_e32 v64, v45
	s_cselect_b32 s22, 0xa800, 0
	v_mul_f32_e32 v66, 0x3fb8aa3b, v202
	v_mul_f32_e32 v67, 0x3fb8aa3b, v203
	v_fma_f32 v42, -v45, v64, 1.0
	v_fmac_f32_e32 v64, v42, v64
	v_div_scale_f32 v42, vcc, 1.0, v44, 1.0
	v_mul_f32_e32 v43, v42, v64
	v_fma_f32 v65, -v45, v43, v42
	v_fmac_f32_e32 v43, v65, v64
	v_fma_f32 v42, -v45, v43, v42
	v_div_fmas_f32 v42, v42, v64, v43
	v_div_fixup_f32 v68, v42, v44, 1.0
	v_pk_add_f32 v[42:43], v[182:183], -1.0 op_sel_hi:[1,0]
	v_pk_add_f32 v[44:45], v[184:185], -1.0 op_sel_hi:[1,0]
	v_pk_add_f32 v[64:65], v[40:41], -1.0 op_sel_hi:[1,0]
	v_pk_fma_f32 v[188:189], v[0:1], v[44:45], 1.0 op_sel_hi:[1,1,0]
	v_pk_fma_f32 v[186:187], v[6:7], v[64:65], 1.0 op_sel_hi:[1,1,0]
	v_pk_fma_f32 v[190:191], v[2:3], v[42:43], 1.0 op_sel_hi:[1,1,0]
	v_mul_f32_e32 v42, 0x3fb8aa3b, v69
	v_mul_f32_e32 v43, 0x3fb8aa3b, v156
	v_mul_f32_e32 v44, 0x3fb8aa3b, v192
	v_mul_f32_e32 v45, 0x3fb8aa3b, v193
	v_mul_f32_e32 v64, 0x3fb8aa3b, v194
	v_mul_f32_e32 v65, 0x3fb8aa3b, v195
	v_pk_mul_f32 v[194:195], v[180:181], v[68:69] op_sel_hi:[1,0]
	v_exp_f32_e32 v42, v42
	v_exp_f32_e32 v43, v43
	v_exp_f32_e32 v44, v44
	v_exp_f32_e32 v45, v45
	v_pk_mul_f32 v[192:193], v[94:95], v[68:69] op_sel_hi:[1,0]
	v_pk_mul_f32 v[180:181], v[70:71], v[68:69] op_sel_hi:[1,0]
	v_pk_mul_f32 v[202:203], v[178:179], v[68:69] op_sel_hi:[1,0]
	v_pk_mul_f32 v[68:69], v[188:189], v[90:91]
	v_pk_mul_f32 v[90:91], v[186:187], v[176:177]
	v_pk_mul_f32 v[186:187], v[194:195], v[40:41]
	v_add_u32_e32 v40, s22, v168
	v_exp_f32_e32 v64, v64
	v_exp_f32_e32 v65, v65
	v_exp_f32_e32 v66, v66
	v_exp_f32_e32 v67, v67
	v_add_u32_e32 v41, v40, v169
	v_pk_mul_f32 v[70:71], v[190:191], v[162:163]
	v_pk_mul_f32 v[88:89], v[88:89], v[92:93]
	v_xor_b32_e32 v95, 0x80000000, v203
	v_xor_b32_e32 v94, 0x80000000, v202
	v_xor_b32_e32 v93, 0x80000000, v181
	v_xor_b32_e32 v92, 0x80000000, v180
	v_xor_b32_e32 v179, 0x80000000, v195
	v_xor_b32_e32 v178, 0x80000000, v194
	v_xor_b32_e32 v177, 0x80000000, v193
	v_xor_b32_e32 v176, 0x80000000, v192
	v_pk_mul_f32 v[182:183], v[202:203], v[182:183]
	v_pk_mul_f32 v[180:181], v[180:181], v[184:185]
	v_pk_mul_f32 v[184:185], v[192:193], v[46:47]
	ds_write_b128 v41, v[60:63]
	ds_write_b128 v41, v[56:59] offset:16
	ds_write_b128 v41, v[42:45] offset:256
	ds_write_b128 v41, v[64:67] offset:272
	ds_write_b128 v41, v[88:91] offset:512
	ds_write_b128 v41, v[68:71] offset:528
	ds_write_b128 v41, v[176:179] offset:768
	ds_write_b128 v41, v[92:95] offset:784
	ds_write_b128 v41, v[184:187] offset:1024
	ds_write_b128 v41, v[180:183] offset:1040
	s_and_saveexec_b64 s[22:23], s[46:47]
	s_cbranch_execz .LBB0_212
	v_add_u32_e32 v40, v40, v170
	ds_write_b128 v40, v[104:107] offset:1280
	ds_write_b128 v40, v[100:103] offset:1296
